# XCD-local fast barrier (runtime-verified bijective WG-residue to XCC map) on 4 row-local seams
# speedup vs baseline: 1.0358x; 1.0183x over previous
_Z10fwd_kernel4Args:
	s_load_dwordx2 s[12:13], s[0:1], 0x100
	s_add_u32 s74, s0, 0x100
	v_and_b32_e32 v218, 0x3ff, v0
	s_mov_b32 s97, s2
	s_addc_u32 s75, s1, 0
	s_mov_b64 s[4:5], s[0:1]
	v_cmp_eq_u32_e32 vcc, 0, v218
	s_and_saveexec_b64 s[2:3], vcc
	s_cbranch_execz .LBB0_3
	s_add_i32 s8, 0, 0x23fc0
	v_mov_b32_e32 v1, 0
	v_mov_b32_e32 v2, s8
	s_add_i32 s8, 0, 0x23fc4
	s_mov_b64 s[6:7], exec
	ds_write_b32 v2, v1
	v_mov_b32_e32 v2, s8
	ds_write_b32 v2, v1
	v_mbcnt_lo_u32_b32 v1, s6, 0
	v_mbcnt_hi_u32_b32 v1, s7, v1
	v_cmp_eq_u32_e32 vcc, 0, v1
	s_getreg_b32 s8, hwreg(HW_REG_XCC_ID, 0, 4)
	s_and_b64 s[10:11], exec, vcc
	s_mov_b64 exec, s[10:11]
	s_cbranch_execz .LBB0_3
	s_load_dwordx2 s[4:5], s[4:5], 0xf0
	s_lshl_b32 s8, s8, 8
	s_and_b32 s8, s8, 0xf00
	v_mov_b32_e32 v1, 0x10000
	s_waitcnt lgkmcnt(0)
	s_add_u32 s4, s4, s8
	s_addc_u32 s5, s5, 0
	s_bcnt1_i32_b64 s6, s[6:7]
	v_mov_b32_e32 v2, s6
	global_atomic_add v1, v2, s[4:5] offset:1024
	s_lshr_b32 s6, s8, 8
	s_and_b32 s7, s97, 7
	s_sub_u32 s4, s4, s8
	s_subb_u32 s5, s5, 0
	s_add_u32 s4, s4, 0x14000
	s_addc_u32 s5, s5, 0
	s_lshl_b32 s7, s7, 2
	s_add_i32 s8, s6, 1
	s_sub_i32 s6, 16, s6
	v_mov_b32_e32 v1, s7
	v_mov_b32_e32 v2, s8
	v_mov_b32_e32 v3, s6
	s_nop 1
	global_atomic_umax v1, v2, s[4:5] offset:64
	global_atomic_umax v1, v3, s[4:5] offset:128

.LBB0_99:
	s_or_b64 exec, exec, s[2:3]
	s_barrier
	v_readlane_b32 s0, v255, 0
	v_readlane_b32 s1, v255, 1
	s_nop 4
	s_load_dword s2, s[0:1], 0x100
	s_load_dwordx2 s[4:5], s[0:1], 0xf0
	s_getreg_b32 s3, hwreg(HW_REG_XCC_ID, 0, 4)
	s_and_b32 s3, s3, 15
	s_lshl_b32 s3, s3, 8
	v_and_b32_e32 v2, 7, v218
	v_lshlrev_b32_e32 v2, 2, v2
	s_waitcnt lgkmcnt(0)
	s_add_u32 s4, s4, 0x14000
	s_addc_u32 s5, s5, 0
	s_nop 1
	global_load_dword v3, v2, s[4:5] offset:64 sc1
	global_load_dword v4, v2, s[4:5] offset:128 sc1
	s_waitcnt vmcnt(0)
	v_add_u32_e32 v4, v3, v4
	v_cmp_ne_u32_e32 vcc, 17, v4
	v_add_u32_e32 v3, -1, v3
	v_lshlrev_b32_e64 v3, v3, 1
	s_nop 1
	v_readlane_b32 s1, v3, 0
	v_readlane_b32 s0, v3, 1
	s_nop 1
	s_or_b32 s1, s1, s0
	v_readlane_b32 s0, v3, 2
	s_nop 1
	s_or_b32 s1, s1, s0
	v_readlane_b32 s0, v3, 3
	s_nop 1
	s_or_b32 s1, s1, s0
	v_readlane_b32 s0, v3, 4
	s_nop 1
	s_or_b32 s1, s1, s0
	v_readlane_b32 s0, v3, 5
	s_nop 1
	s_or_b32 s1, s1, s0
	v_readlane_b32 s0, v3, 6
	s_nop 1
	s_or_b32 s1, s1, s0
	v_readlane_b32 s0, v3, 7
	s_nop 1
	s_or_b32 s1, s1, s0
	s_bcnt1_i32_b32 s0, s1
	s_add_u32 s4, s4, s3
	s_addc_u32 s5, s5, 0
	s_add_u32 s4, s4, 0x100
	s_addc_u32 s5, s5, 0
	s_cmp_eq_u32 s0, 8
	s_cselect_b32 s1, 32, 0
	s_cmp_eq_u64 vcc, 0
	s_cselect_b32 s1, s1, 0
	s_cmpk_eq_u32 s2, 0x100
	s_cselect_b32 s1, s1, 0
	v_writelane_b32 v255, s1, 40
	v_writelane_b32 v255, s4, 41
	v_writelane_b32 v255, s5, 42
	s_load_dword s0, s[78:79], 0x108
	s_add_i32 s2, 0, 0x1c800
	v_writelane_b32 v255, s2, 2
	s_add_i32 s2, 0, 0x1e020
	v_writelane_b32 v255, s2, 3
	s_add_i32 s2, 0, 0x1e820
	v_writelane_b32 v255, s2, 4
	s_add_i32 s2, 0, 0x1e3a0
	s_mul_i32 s1, s77, s76
	v_writelane_b32 v255, s2, 5
	s_waitcnt lgkmcnt(0)
	s_mul_i32 s77, s1, s0
	v_writelane_b32 v255, s97, 6
	s_add_i32 s84, 0, 0x23fc0
	v_writelane_b32 v255, s77, 7
	s_add_i32 s85, 0, 0x23fc4
	v_writelane_b32 v255, s84, 8
	s_mov_b32 s81, 0
	s_mov_b64 s[12:13], -1
	s_movk_i32 s68, 0xb00
	s_movk_i32 s0, 0x2000
	s_mov_b32 s69, 0x1fffe0
	s_movk_i32 s70, 0x161
	s_mov_b32 s71, 0x10000
	v_mov_b32_e32 v0, 0
	s_mov_b64 s[72:73], 0x40000
	s_movk_i32 s1, 0x3c0
	s_mov_b32 s74, 0x18000
	s_mov_b64 s[94:95], 0x80
	s_mov_b32 s75, 0x8000
	s_movk_i32 s82, 0x80
	v_mov_b32_e32 v219, 0x358637bd
	s_mov_b32 s86, 0x800000
	s_movk_i32 s83, 0x1600
	s_mov_b64 s[90:91], 0x10000
	v_mov_b32_e32 v254, 0x2000
	v_mov_b32_e32 v225, 0x13000
	v_mov_b32_e32 v253, 1
	s_mov_b32 s87, 0x40000
	s_mov_b32 s92, 0x48000
	s_mov_b32 s93, 0x50000
	s_movk_i32 s33, 0x1000
	s_movk_i32 s88, 0x3000
	s_movk_i32 s89, 0x101
	v_mov_b32_e32 v224, 0x260
	v_mov_b64_e32 v[200:201], 0x200
	v_mov_b64_e32 v[202:203], 0x1ff
	v_mov_b32_e32 v226, 0x80
	v_mov_b32_e32 v227, 0xfe0
	s_mov_b32 s6, 0
	s_mov_b32 s96, 0x3e38aa3b
	v_writelane_b32 v255, s85, 9
	s_branch .LBB0_102
